# v34 recipe with the attention LDS operand fetch-ahead depth 7 (was 6)
# baseline (speedup 1.0000x reference)
; template <int TYPE>
; __device__ __forceinline__ void attn_item(const Ctx& a, int b, int h, int qt, LAS unsigned char* lds) {
;     ...
; #pragma unroll
;         for (int kk = 0; kk < NKK; ++kk)
; #pragma unroll
;             for (int sub = 0; sub < 2; ++sub)
;                 if (act[sub]) {
; #pragma unroll
;                     for (int kb = 0; kb < 2; ++kb) {
;                         bf16x8 ka = *(const LAS bf16x8*)(Kt + (sub * 64 + kb * 32 + l32) * KLD + kk * 16 + hb * 8);
;                         s[sub][kb] = __builtin_amdgcn_mfma_f32_32x32x16_bf16(ka, Q[kk], s[sub][kb], 0, 0, 0);
;                     }
;                 }
; #pragma unroll
;         for (int sub = 0; sub < 2; ++sub) {
;             if (!act[sub]) continue;
;             const int kt = kp * 2 + sub, kloc = kt - qt * 4;
;             if (kloc >= 0) {
; #pragma unroll
;                 for (int kb = 0; kb < 2; ++kb)
; #pragma unroll
;                     for (int r = 0; r < 16; ++r) { int kabs = kt * 64 + kb * 32 + (r >> 2) * 8 + hb * 4 + (r & 3); if (kabs > qrow) s[sub][kb][r] = -1e30f; }
;             } else if (TYPE == 1) {
;                 if (!((qmask >> (kt >> 2)) & 1u)) {
; #pragma unroll
;                     for (int kb = 0; kb < 2; ++kb)
; #pragma unroll
;                         for (int r = 0; r < 16; ++r) s[sub][kb][r] = -1e30f;
;                 }
;             }
;             float mx = -1e30f;
; #pragma unroll
;             for (int kb = 0; kb < 2; ++kb)
; #pragma unroll
;                 for (int r = 0; r < 16; ++r) mx = fmaxf(mx, s[sub][kb][r]);
;             mx = fmaxf(mx, __shfl_xor(mx, 32));
;             const float delta = mrun - mref;
;             const bool bump = (mx - delta) > 8.f;
;             const bool rare = __builtin_amdgcn_ballot_w64(bump || delta != 0.f) != 0ull;
;             float fpost = 1.f;
;             if (rare) {
;                 const float mnew = bump ? mref + mx : mrun;
;                 const float pre = __builtin_amdgcn_exp2f(delta);
;                 fpost = __builtin_amdgcn_exp2f(mref - mnew);
;                 mrun = mnew;
;                 lrun *= pre;
; #pragma unroll
;                 for (int db = 0; db < 2; ++db)
; #pragma unroll
;                     for (int r = 0; r < 16; ++r) oacc[db][r] *= pre;
;             }
;             float ps = 0.f;
; #pragma unroll
;             for (int kb = 0; kb < 2; ++kb)
; #pragma unroll
.Lat0_loop:
	s_add_u32 s8, s26, 2
	s_cmp_ge_u32 s8, s30
	s_cselect_b32 s57, 1, 0
	s_cmp_eq_u32 s57, 1
	s_cbranch_scc1 .Lat0_gen
	s_cmp_lg_u64 s[36:37], 0
	s_cbranch_scc1 .Lat0_gen
	v_mov_b32 v211, v0
	ds_read_b128 v[146:149], v190 offset:0
	ds_read_b128 v[150:153], v190 offset:6656
	ds_read_b128 v[154:157], v190 offset:32
	ds_read_b128 v[158:161], v190 offset:6688
	ds_read_b128 v[162:165], v190 offset:64
	ds_read_b128 v[166:169], v190 offset:6720
	ds_read_b128 v[170:173], v190 offset:96
	s_waitcnt lgkmcnt(6)
	v_mfma_f32_32x32x16_bf16 v[48:63], v[146:149], v[112:115], 0
	ds_read_b128 v[174:177], v190 offset:6752
	s_waitcnt lgkmcnt(6)
	v_mfma_f32_32x32x16_bf16 v[64:79], v[150:153], v[112:115], 0
	ds_read_b128 v[146:149], v190 offset:128
	s_waitcnt lgkmcnt(6)
	v_mfma_f32_32x32x16_bf16 v[48:63], v[154:157], v[116:119], v[48:63]
	ds_read_b128 v[150:153], v190 offset:6784
	s_waitcnt lgkmcnt(6)
	v_mfma_f32_32x32x16_bf16 v[64:79], v[158:161], v[116:119], v[64:79]
	ds_read_b128 v[154:157], v190 offset:160
	s_waitcnt lgkmcnt(6)
	v_mfma_f32_32x32x16_bf16 v[48:63], v[162:165], v[120:123], v[48:63]
	ds_read_b128 v[158:161], v190 offset:6816
	s_waitcnt lgkmcnt(6)
	v_mfma_f32_32x32x16_bf16 v[64:79], v[166:169], v[120:123], v[64:79]
	ds_read_b128 v[162:165], v190 offset:13312
	s_waitcnt lgkmcnt(6)
	v_mfma_f32_32x32x16_bf16 v[48:63], v[170:173], v[124:127], v[48:63]
	ds_read_b128 v[166:169], v190 offset:19968
	s_waitcnt lgkmcnt(6)
	v_mfma_f32_32x32x16_bf16 v[64:79], v[174:177], v[124:127], v[64:79]
	ds_read_b128 v[170:173], v190 offset:13344
	s_waitcnt lgkmcnt(6)
	v_mfma_f32_32x32x16_bf16 v[48:63], v[146:149], v[128:131], v[48:63]
	ds_read_b128 v[174:177], v190 offset:20000
	s_waitcnt lgkmcnt(6)
	v_mfma_f32_32x32x16_bf16 v[64:79], v[150:153], v[128:131], v[64:79]
	ds_read_b128 v[146:149], v190 offset:13376
	s_waitcnt lgkmcnt(6)
	v_mfma_f32_32x32x16_bf16 v[48:63], v[154:157], v[132:135], v[48:63]
	ds_read_b128 v[150:153], v190 offset:20032
	s_waitcnt lgkmcnt(6)
	v_mfma_f32_32x32x16_bf16 v[64:79], v[158:161], v[132:135], v[64:79]
	ds_read_b128 v[154:157], v190 offset:13408
	s_waitcnt vmcnt(0)
	s_waitcnt lgkmcnt(6)
	v_mfma_f32_32x32x16_bf16 v[80:95], v[162:165], v[112:115], 0
	ds_read_b128 v[158:161], v190 offset:20064
	s_nop 3
	v_max3_f32 v211, v211, v48, v49
	v_exp_f32 v48, v48
	v_exp_f32 v49, v49
	v_max3_f32 v211, v211, v50, v51
	v_exp_f32 v50, v50
	v_exp_f32 v51, v51
	v_add_f32 v188, v48, v49
	v_cvt_pk_bf16_f32 v48, v48, v49
	s_waitcnt lgkmcnt(6)
	v_mfma_f32_32x32x16_bf16 v[96:111], v[166:169], v[112:115], 0
	ds_write_b128 v193, v[2:5]
	ds_read_b128 v[162:165], v190 offset:13440
	v_max3_f32 v211, v211, v52, v53
	v_exp_f32 v52, v52
	v_exp_f32 v53, v53
	v_add_f32 v188, v188, v50
	v_add_f32 v188, v188, v51
	v_cvt_pk_bf16_f32 v49, v50, v51
	v_max3_f32 v211, v211, v54, v55
	v_exp_f32 v54, v54
	s_waitcnt lgkmcnt(7)
	v_mfma_f32_32x32x16_bf16 v[80:95], v[170:173], v[116:119], v[80:95]
	ds_read_b128 v[166:169], v190 offset:20096
	v_exp_f32 v55, v55
	v_add_f32 v188, v188, v52
	v_add_f32 v188, v188, v53
	v_cvt_pk_bf16_f32 v50, v52, v53
	v_max3_f32 v211, v211, v56, v57
	v_exp_f32 v56, v56
	v_exp_f32 v57, v57
	v_add_f32 v188, v188, v54
	s_waitcnt lgkmcnt(7)
	v_mfma_f32_32x32x16_bf16 v[96:111], v[174:177], v[116:119], v[96:111]
	ds_write_b128 v193, v[10:13] offset:13312
	ds_read_b128 v[170:173], v190 offset:13472
	v_add_f32 v188, v188, v55
	v_cvt_pk_bf16_f32 v51, v54, v55
	v_max3_f32 v211, v211, v58, v59
	v_exp_f32 v58, v58
	v_exp_f32 v59, v59
	v_add_f32 v188, v188, v56
	v_add_f32 v188, v188, v57
	v_cvt_pk_bf16_f32 v52, v56, v57
	s_waitcnt lgkmcnt(8)
	v_mfma_f32_32x32x16_bf16 v[80:95], v[146:149], v[120:123], v[80:95]
	ds_read_b128 v[174:177], v190 offset:20128
	v_max3_f32 v211, v211, v60, v61
	v_exp_f32 v60, v60
	v_exp_f32 v61, v61
	v_add_f32 v188, v188, v58
	v_add_f32 v188, v188, v59
	v_cvt_pk_bf16_f32 v53, v58, v59
	v_max3_f32 v211, v211, v62, v63
	v_exp_f32 v62, v62
	s_waitcnt lgkmcnt(8)
	v_mfma_f32_32x32x16_bf16 v[96:111], v[150:153], v[120:123], v[96:111]
	ds_write_b128 v200, v[6:9]
	ds_read_b64_tr_b16 v[146:147], v191 offset:0
	ds_read_b64_tr_b16 v[148:149], v191 offset:1024
	v_exp_f32 v63, v63
	v_add_f32 v188, v188, v60
	v_add_f32 v188, v188, v61
	v_cvt_pk_bf16_f32 v54, v60, v61
	v_add_f32 v188, v188, v62
	v_add_f32 v188, v188, v63
	v_cvt_pk_bf16_f32 v55, v62, v63
	v_max3_f32 v211, v211, v64, v65
	s_waitcnt lgkmcnt(10)
	v_mfma_f32_32x32x16_bf16 v[80:95], v[154:157], v[124:127], v[80:95]
	ds_read_b64_tr_b16 v[150:151], v192 offset:0
	ds_read_b64_tr_b16 v[152:153], v192 offset:1024
	v_exp_f32 v64, v64
	v_exp_f32 v65, v65
	v_max3_f32 v211, v211, v66, v67
	v_exp_f32 v66, v66
	v_exp_f32 v67, v67
	v_add_f32 v188, v188, v64
	v_add_f32 v188, v188, v65
	v_cvt_pk_bf16_f32 v64, v64, v65
	s_waitcnt lgkmcnt(11)
	v_mfma_f32_32x32x16_bf16 v[96:111], v[158:161], v[124:127], v[96:111]
	ds_write_b128 v200, v[136:139] offset:8192
	ds_read_b64_tr_b16 v[154:155], v191 offset:2048
	ds_read_b64_tr_b16 v[156:157], v191 offset:3072
	v_max3_f32 v211, v211, v68, v69
	v_exp_f32 v68, v68
	v_exp_f32 v69, v69
	v_add_f32 v188, v188, v66
	v_add_f32 v188, v188, v67
	v_cvt_pk_bf16_f32 v65, v66, v67
	v_max3_f32 v211, v211, v70, v71
	v_exp_f32 v70, v70
	s_waitcnt lgkmcnt(12)
	v_mfma_f32_32x32x16_bf16 v[80:95], v[162:165], v[128:131], v[80:95]
	ds_read_b64_tr_b16 v[158:159], v192 offset:2048
	ds_read_b64_tr_b16 v[160:161], v192 offset:3072
	v_exp_f32 v71, v71
	v_add_f32 v188, v188, v68
	v_add_f32 v188, v188, v69
	v_cvt_pk_bf16_f32 v66, v68, v69
	v_max3_f32 v211, v211, v72, v73
	v_exp_f32 v72, v72
	v_exp_f32 v73, v73
	v_add_f32 v188, v188, v70
	s_waitcnt lgkmcnt(13)
; template <int TYPE>
; __device__ __forceinline__ void attn_item(const Ctx& a, int b, int h, int qt, LAS unsigned char* lds) {
;     ...
;             for (int kb = 0; kb < 2; ++kb)
; #pragma unroll
;                 for (int r = 0; r < 16; ++r) { float p = __builtin_amdgcn_exp2f(s[sub][kb][r]); s[sub][kb][r] = p; ps += p; }
;             lrun += ps;
; #pragma unroll
;             for (int kb = 0; kb < 2; ++kb)
; #pragma unroll
;                 for (int c = 0; c < 2; ++c) {
;                     bf16x8 pb = pack8(s[sub][kb], c);
; #pragma unroll
;                     for (int db = 0; db < 2; ++db)
;                         oacc[db] = __builtin_amdgcn_mfma_f32_32x32x16_bf16(lds_a2(VT + (db * 32 + l32) * VLD + sub * 64 + kb * 32 + c * 16 + hb * 4), pb, oacc[db], 0, 0, 0);
;                 }
;             if (rare) {
;                 lrun *= fpost;
; #pragma unroll
;                 for (int db = 0; db < 2; ++db)
; #pragma unroll
;                     for (int r = 0; r < 16; ++r) oacc[db][r] *= fpost;
;             }
;         }
;         if (kp + 1 < npair) AT_STORE(bufi ^ 1);
	v_mfma_f32_32x32x16_bf16 v[96:111], v[166:169], v[128:131], v[96:111]
	ds_write_b128 v201, v[140:143]
	ds_read_b64_tr_b16 v[162:163], v191 offset:4096
	ds_read_b64_tr_b16 v[164:165], v191 offset:5120
	v_add_f32 v188, v188, v71
	v_cvt_pk_bf16_f32 v67, v70, v71
	v_max3_f32 v211, v211, v74, v75
	v_exp_f32 v74, v74
	v_exp_f32 v75, v75
	v_add_f32 v188, v188, v72
	v_add_f32 v188, v188, v73
	v_cvt_pk_bf16_f32 v68, v72, v73
	s_waitcnt lgkmcnt(14)
	v_mfma_f32_32x32x16_bf16 v[80:95], v[170:173], v[132:135], v[80:95]
	ds_read_b64_tr_b16 v[166:167], v192 offset:4096
	ds_read_b64_tr_b16 v[168:169], v192 offset:5120
	v_max3_f32 v211, v211, v76, v77
	v_exp_f32 v76, v76
	v_exp_f32 v77, v77
	v_add_f32 v188, v188, v74
	v_add_f32 v188, v188, v75
	v_cvt_pk_bf16_f32 v69, v74, v75
	v_max3_f32 v211, v211, v78, v79
	v_exp_f32 v78, v78
	s_waitcnt lgkmcnt(15)
	v_mfma_f32_32x32x16_bf16 v[96:111], v[174:177], v[132:135], v[96:111]
	ds_read_b64_tr_b16 v[170:171], v191 offset:6144
	ds_read_b64_tr_b16 v[172:173], v191 offset:7168
	v_exp_f32 v79, v79
	v_add_f32 v188, v188, v76
	v_add_f32 v188, v188, v77
	v_cvt_pk_bf16_f32 v70, v76, v77
	v_add_f32 v188, v188, v78
	v_add_f32 v188, v188, v79
	v_cvt_pk_bf16_f32 v71, v78, v79
	v_add_f32 v206, v206, v188
	s_cmp_eq_u32 s13, 2
	s_cselect_b32 s8, 0x1f800, 0
	s_sub_u32 s8, 0xa800, s8
	s_add_u32 s13, s13, 1
	s_cmp_eq_u32 s13, 3
	s_cselect_b32 s13, 0, s13
	s_waitcnt lgkmcnt(0)
	s_add_u32 s9, s26, 2
	s_cmp_lt_u32 s9, s30
	s_cbranch_scc0 .Lat0_mid1
	global_load_dwordx4 v[2:5], v184, s[52:53]
	global_load_dwordx4 v[6:9], v184, s[52:53] offset:128
	global_load_dwordx4 v[10:13], v185, s[52:53]
	global_load_dwordx4 v[136:139], v185, s[52:53] offset:128
	global_load_dwordx4 v[140:143], v186, s[54:55]
	s_add_u32 s52, s52, 0x70000
	s_addc_u32 s53, s53, 0
	s_add_u32 s54, s54, 0x10000
	s_addc_u32 s55, s55, 0
; template <int TYPE>
; __device__ __forceinline__ void attn_item(const Ctx& a, int b, int h, int qt, LAS unsigned char* lds) {
;     ...
;             for (int kb = 0; kb < 2; ++kb)
; #pragma unroll
;                 for (int c = 0; c < 2; ++c) {
;                     bf16x8 pb = pack8(s[sub][kb], c);
; #pragma unroll
;                     for (int db = 0; db < 2; ++db)
;                         oacc[db] = __builtin_amdgcn_mfma_f32_32x32x16_bf16(lds_a2(VT + (db * 32 + l32) * VLD + sub * 64 + kb * 32 + c * 16 + hb * 4), pb, oacc[db], 0, 0, 0);
;                 }
;             if (rare) {
;                 lrun *= fpost;
; #pragma unroll
;                 for (int db = 0; db < 2; ++db)
; #pragma unroll
;                     for (int r = 0; r < 16; ++r) oacc[db][r] *= fpost;
;             }
.Lat0_mid1:
	v_add_u32 v193, s8, v193
	v_add_u32 v200, s8, v200
	v_add_u32 v201, s8, v201
	s_barrier
	s_nop 7
	v_mfma_f32_32x32x16_bf16 v[16:31], v[146:149], v[48:51], v[16:31]
	ds_read_b64_tr_b16 v[174:175], v192 offset:6144
	ds_read_b64_tr_b16 v[176:177], v192 offset:7168
	v_max3_f32 v211, v211, v80, v81
	v_exp_f32 v80, v80
	v_exp_f32 v81, v81
	v_max3_f32 v211, v211, v82, v83
	v_exp_f32 v82, v82
	v_exp_f32 v83, v83
	v_add_f32 v188, v80, v81
	v_cvt_pk_bf16_f32 v80, v80, v81
	v_max3_f32 v211, v211, v84, v85
	v_exp_f32 v84, v84
	v_exp_f32 v85, v85
	v_add_f32 v188, v188, v82
	v_mfma_f32_32x32x16_bf16 v[32:47], v[150:153], v[48:51], v[32:47]
	ds_read_b64_tr_b16 v[146:147], v191 offset:8192
	ds_read_b64_tr_b16 v[148:149], v191 offset:9216
	v_add_f32 v188, v188, v83
	v_cvt_pk_bf16_f32 v81, v82, v83
	v_max3_f32 v211, v211, v86, v87
	v_exp_f32 v86, v86
	v_exp_f32 v87, v87
	v_add_f32 v188, v188, v84
	v_add_f32 v188, v188, v85
	v_cvt_pk_bf16_f32 v82, v84, v85
	v_max3_f32 v211, v211, v88, v89
	v_exp_f32 v88, v88
	v_exp_f32 v89, v89
	v_add_f32 v188, v188, v86
	v_mfma_f32_32x32x16_bf16 v[16:31], v[154:157], v[52:55], v[16:31]
	ds_read_b64_tr_b16 v[150:151], v192 offset:8192
	ds_read_b64_tr_b16 v[152:153], v192 offset:9216
	v_add_f32 v188, v188, v87
	v_cvt_pk_bf16_f32 v83, v86, v87
	v_max3_f32 v211, v211, v90, v91
	v_exp_f32 v90, v90
	v_exp_f32 v91, v91
	v_add_f32 v188, v188, v88
	v_add_f32 v188, v188, v89
	v_cvt_pk_bf16_f32 v84, v88, v89
	v_max3_f32 v211, v211, v92, v93
	v_exp_f32 v92, v92
	v_exp_f32 v93, v93
	v_add_f32 v188, v188, v90
	v_mfma_f32_32x32x16_bf16 v[32:47], v[158:161], v[52:55], v[32:47]
	ds_read_b64_tr_b16 v[154:155], v191 offset:10240
	ds_read_b64_tr_b16 v[156:157], v191 offset:11264
	v_add_f32 v188, v188, v91
	v_cvt_pk_bf16_f32 v85, v90, v91
	v_max3_f32 v211, v211, v94, v95
	v_exp_f32 v94, v94
	v_exp_f32 v95, v95
	v_add_f32 v188, v188, v92
	v_add_f32 v188, v188, v93
	v_cvt_pk_bf16_f32 v86, v92, v93
	v_add_f32 v188, v188, v94
	v_add_f32 v188, v188, v95
	v_cvt_pk_bf16_f32 v87, v94, v95
	v_max3_f32 v211, v211, v96, v97
	v_mfma_f32_32x32x16_bf16 v[16:31], v[162:165], v[64:67], v[16:31]
	ds_read_b64_tr_b16 v[158:159], v192 offset:10240
	ds_read_b64_tr_b16 v[160:161], v192 offset:11264
	v_exp_f32 v96, v96
	v_exp_f32 v97, v97
	v_max3_f32 v211, v211, v98, v99
	v_exp_f32 v98, v98
	v_exp_f32 v99, v99
	v_add_f32 v188, v188, v96
	v_add_f32 v188, v188, v97
	v_cvt_pk_bf16_f32 v96, v96, v97
	v_max3_f32 v211, v211, v100, v101
	v_exp_f32 v100, v100
	v_exp_f32 v101, v101
	v_add_f32 v188, v188, v98
	v_mfma_f32_32x32x16_bf16 v[32:47], v[166:169], v[64:67], v[32:47]
	ds_read_b64_tr_b16 v[162:163], v191 offset:12288
	ds_read_b64_tr_b16 v[164:165], v191 offset:13312
	v_add_f32 v188, v188, v99
	v_cvt_pk_bf16_f32 v97, v98, v99
	v_max3_f32 v211, v211, v102, v103
	v_exp_f32 v102, v102
	v_exp_f32 v103, v103
	v_add_f32 v188, v188, v100
	v_add_f32 v188, v188, v101
	v_cvt_pk_bf16_f32 v98, v100, v101
	v_max3_f32 v211, v211, v104, v105
	v_exp_f32 v104, v104
	v_exp_f32 v105, v105
	v_add_f32 v188, v188, v102
	v_mfma_f32_32x32x16_bf16 v[16:31], v[170:173], v[68:71], v[16:31]
	ds_read_b64_tr_b16 v[166:167], v192 offset:12288
	ds_read_b64_tr_b16 v[168:169], v192 offset:13312
	v_add_f32 v188, v188, v103
	v_cvt_pk_bf16_f32 v99, v102, v103
	v_max3_f32 v211, v211, v106, v107
	v_exp_f32 v106, v106
	v_exp_f32 v107, v107
	v_add_f32 v188, v188, v104
	v_add_f32 v188, v188, v105
	v_cvt_pk_bf16_f32 v100, v104, v105
	v_max3_f32 v211, v211, v108, v109
	v_exp_f32 v108, v108
	v_exp_f32 v109, v109
	v_add_f32 v188, v188, v106
	s_waitcnt lgkmcnt(12)
	v_mfma_f32_32x32x16_bf16 v[32:47], v[174:177], v[68:71], v[32:47]
	ds_read_b64_tr_b16 v[170:171], v191 offset:14336
	ds_read_b64_tr_b16 v[172:173], v191 offset:15360
	v_add_f32 v188, v188, v107
	v_cvt_pk_bf16_f32 v101, v106, v107
	v_max3_f32 v211, v211, v110, v111
	v_exp_f32 v110, v110
	v_exp_f32 v111, v111
	v_add_f32 v188, v188, v108
	v_add_f32 v188, v188, v109
	v_cvt_pk_bf16_f32 v102, v108, v109
	v_add_f32 v188, v188, v110
	v_add_f32 v188, v188, v111
	v_cvt_pk_bf16_f32 v103, v110, v111
	v_add_f32 v206, v206, v188
	s_waitcnt lgkmcnt(12)
	v_mfma_f32_32x32x16_bf16 v[16:31], v[146:149], v[80:83], v[16:31]
	ds_read_b64_tr_b16 v[174:175], v192 offset:14336
	ds_read_b64_tr_b16 v[176:177], v192 offset:15360
	s_waitcnt lgkmcnt(12)
	v_mfma_f32_32x32x16_bf16 v[32:47], v[150:153], v[80:83], v[32:47]
	s_waitcnt lgkmcnt(10)
	v_mfma_f32_32x32x16_bf16 v[16:31], v[154:157], v[84:87], v[16:31]
	s_waitcnt lgkmcnt(8)
	v_mfma_f32_32x32x16_bf16 v[32:47], v[158:161], v[84:87], v[32:47]
	s_waitcnt lgkmcnt(6)
	v_mfma_f32_32x32x16_bf16 v[16:31], v[162:165], v[96:99], v[16:31]
	s_waitcnt lgkmcnt(4)
	v_mfma_f32_32x32x16_bf16 v[32:47], v[166:169], v[96:99], v[32:47]
	s_waitcnt lgkmcnt(2)
	v_mfma_f32_32x32x16_bf16 v[16:31], v[170:173], v[100:103], v[16:31]
	s_waitcnt lgkmcnt(0)
	v_mfma_f32_32x32x16_bf16 v[32:47], v[174:177], v[100:103], v[32:47]
	v_cmp_gt_f32_e64 s[40:41], v211, v207
	s_cmp_lg_u64 s[40:41], 0
	s_cbranch_scc0 .Lat0_pairend
	v_mov_b32 v1, v211
	s_nop 1
	v_permlane32_swap_b32 v1, v211
	v_max_f32 v1, v1, v211
	v_cmp_gt_f32 vcc, v1, v207
	s_nop 1
	v_cndmask_b32 v14, v205, v1, vcc
	v_sub_f32 v15, v205, v14
	v_exp_f32 v15, v15
	v_mov_b32 v205, v14
	v_add_f32 v207, 0x41000000, v14
	v_mul_f32 v16, v16, v15
	v_mul_f32 v17, v17, v15
	v_mul_f32 v18, v18, v15
	v_mul_f32 v19, v19, v15
	v_mul_f32 v20, v20, v15
	v_mul_f32 v21, v21, v15
	v_mul_f32 v22, v22, v15
	v_mul_f32 v23, v23, v15
	v_mul_f32 v24, v24, v15
	v_mul_f32 v25, v25, v15
	v_mul_f32 v26, v26, v15
	v_mul_f32 v27, v27, v15
	v_mul_f32 v28, v28, v15
	v_mul_f32 v29, v29, v15
	v_mul_f32 v30, v30, v15
	v_mul_f32 v31, v31, v15
	v_mul_f32 v32, v32, v15
	v_mul_f32 v33, v33, v15
	v_mul_f32 v34, v34, v15
	v_mul_f32 v35, v35, v15
	v_mul_f32 v36, v36, v15
	v_mul_f32 v37, v37, v15
	v_mul_f32 v38, v38, v15
	v_mul_f32 v39, v39, v15
	v_mul_f32 v40, v40, v15
	v_mul_f32 v41, v41, v15
	v_mul_f32 v42, v42, v15
	v_mul_f32 v43, v43, v15
	v_mul_f32 v44, v44, v15
	v_mul_f32 v45, v45, v15
	v_mul_f32 v46, v46, v15
	v_mul_f32 v47, v47, v15
	v_mul_f32 v206, v206, v15
	v_cmp_neq_f32_e64 s[36:37], 0, v205
	s_branch .Lat0_pairend

; template <int TYPE>
; __device__ __forceinline__ void attn_item(const Ctx& a, int b, int h, int qt, LAS unsigned char* lds) {
;     ...
;         for (int sub = 0; sub < 2; ++sub) {
;             const int kloc = kp * 2 + sub - qt * 4;
;             act[sub] = (kloc < 0) || (kloc * 64 <= wv * 32 + 31);
;             if (TYPE == 1 && kloc < 0) act[sub] = __builtin_amdgcn_ballot_w64((qmask >> ((kp * 2 + sub) >> 2)) & 1u) != 0ull;
; #pragma unroll
;             for (int kb = 0; kb < 2; ++kb)
; #pragma unroll
;                 for (int r = 0; r < 16; ++r) s[sub][kb][r] = -mref;
;         }
; #pragma unroll
;         for (int kk = 0; kk < NKK; ++kk)
; #pragma unroll
;             for (int sub = 0; sub < 2; ++sub)
;                 if (act[sub]) {
; #pragma unroll
;                     for (int kb = 0; kb < 2; ++kb) {
;                         bf16x8 ka = *(const LAS bf16x8*)(Kt + (sub * 64 + kb * 32 + l32) * KLD + kk * 16 + hb * 8);
;                         s[sub][kb] = __builtin_amdgcn_mfma_f32_32x32x16_bf16(ka, Q[kk], s[sub][kb], 0, 0, 0);
;                     }
;                 }
; #pragma unroll
;         for (int sub = 0; sub < 2; ++sub) {
;             if (!act[sub]) continue;
;             const int kt = kp * 2 + sub, kloc = kt - qt * 4;
;             if (kloc >= 0) {
; #pragma unroll
;                 for (int kb = 0; kb < 2; ++kb)
; #pragma unroll
;                     for (int r = 0; r < 16; ++r) { int kabs = kt * 64 + kb * 32 + (r >> 2) * 8 + hb * 4 + (r & 3); if (kabs > qrow) s[sub][kb][r] = -1e30f; }
;             } else if (TYPE == 1) {
;                 if (!((qmask >> (kt >> 2)) & 1u)) {
; #pragma unroll
;                     for (int kb = 0; kb < 2; ++kb)
; #pragma unroll
;                         for (int r = 0; r < 16; ++r) s[sub][kb][r] = -1e30f;
;                 }
;             }
;             float mx = -1e30f;
; #pragma unroll
;             for (int kb = 0; kb < 2; ++kb)
; #pragma unroll
;                 for (int r = 0; r < 16; ++r) mx = fmaxf(mx, s[sub][kb][r]);
;             mx = fmaxf(mx, __shfl_xor(mx, 32));
;             const float delta = mrun - mref;
;             const bool bump = (mx - delta) > 8.f;
;             const bool rare = __builtin_amdgcn_ballot_w64(bump || delta != 0.f) != 0ull;
;             float fpost = 1.f;
;             if (rare) {
;                 const float mnew = bump ? mref + mx : mrun;
.Lat1_loop:
	s_add_u32 s8, s26, 2
	s_cmp_ge_u32 s8, s30
	s_cselect_b32 s57, 1, 0
	s_lshr_b32 s8, s26, 1
	v_lshrrev_b32 v1, s8, v209
	v_and_b32 v1, 1, v1
	v_sub_u32 v210, 0, v1
	v_cmp_ne_u32_e64 s[38:39], 0, v1
	s_cmp_eq_u32 s57, 1
	s_cbranch_scc1 .Lat1_gen
	s_cmp_eq_u64 s[38:39], 0
	s_cbranch_scc1 .Lat1_skip
	s_cmp_lg_u64 s[36:37], 0
	s_cbranch_scc1 .Lat1_gen
	v_mov_b32 v211, v0
	ds_read_b128 v[146:149], v190 offset:0
	ds_read_b128 v[150:153], v190 offset:4608
	ds_read_b128 v[154:157], v190 offset:32
	ds_read_b128 v[158:161], v190 offset:4640
	ds_read_b128 v[162:165], v190 offset:64
	ds_read_b128 v[166:169], v190 offset:4672
	ds_read_b128 v[170:173], v190 offset:96
	s_waitcnt lgkmcnt(6)
	v_mfma_f32_32x32x16_bf16 v[48:63], v[146:149], v[112:115], 0
	ds_read_b128 v[174:177], v190 offset:4704
	s_waitcnt lgkmcnt(6)
	v_mfma_f32_32x32x16_bf16 v[64:79], v[150:153], v[112:115], 0
	ds_read_b128 v[146:149], v190 offset:9216
	s_waitcnt lgkmcnt(6)
	v_mfma_f32_32x32x16_bf16 v[48:63], v[154:157], v[116:119], v[48:63]
	ds_read_b128 v[150:153], v190 offset:13824
	s_waitcnt lgkmcnt(6)
	v_mfma_f32_32x32x16_bf16 v[64:79], v[158:161], v[116:119], v[64:79]
	ds_read_b128 v[154:157], v190 offset:9248
	s_waitcnt lgkmcnt(6)
	v_mfma_f32_32x32x16_bf16 v[48:63], v[162:165], v[120:123], v[48:63]
	ds_read_b128 v[158:161], v190 offset:13856
	s_waitcnt lgkmcnt(6)
	v_mfma_f32_32x32x16_bf16 v[64:79], v[166:169], v[120:123], v[64:79]
	ds_read_b128 v[162:165], v190 offset:9280
	s_waitcnt lgkmcnt(6)
	v_mfma_f32_32x32x16_bf16 v[48:63], v[170:173], v[124:127], v[48:63]
	ds_read_b128 v[166:169], v190 offset:13888
	s_waitcnt lgkmcnt(6)
	v_mfma_f32_32x32x16_bf16 v[64:79], v[174:177], v[124:127], v[64:79]
	ds_read_b128 v[170:173], v190 offset:9312
	s_waitcnt vmcnt(0)
	s_waitcnt lgkmcnt(6)
	v_mfma_f32_32x32x16_bf16 v[80:95], v[146:149], v[112:115], 0
	ds_read_b128 v[174:177], v190 offset:13920
	s_nop 3
	v_max3_f32 v211, v211, v48, v49
	v_exp_f32 v48, v48
	v_exp_f32 v49, v49
	v_max3_f32 v211, v211, v50, v51
	v_exp_f32 v50, v50
	v_exp_f32 v51, v51
	v_add_f32 v188, v48, v49
	v_cvt_pk_bf16_f32 v48, v48, v49
	v_and_b32 v48, v48, v210
	v_max3_f32 v211, v211, v52, v53
	v_exp_f32 v52, v52
	v_exp_f32 v53, v53
	v_add_f32 v188, v188, v50
	v_add_f32 v188, v188, v51
	s_waitcnt lgkmcnt(6)
	v_mfma_f32_32x32x16_bf16 v[96:111], v[150:153], v[112:115], 0
	ds_write_b128 v193, v[2:5]
	ds_read_b64_tr_b16 v[146:147], v191 offset:0
	ds_read_b64_tr_b16 v[148:149], v191 offset:1024
	v_cvt_pk_bf16_f32 v49, v50, v51
	v_and_b32 v49, v49, v210
	v_max3_f32 v211, v211, v54, v55
	v_exp_f32 v54, v54
	v_exp_f32 v55, v55
	v_add_f32 v188, v188, v52
	v_add_f32 v188, v188, v53
	v_cvt_pk_bf16_f32 v50, v52, v53
	v_and_b32 v50, v50, v210
	v_max3_f32 v211, v211, v56, v57
	v_exp_f32 v56, v56
	v_exp_f32 v57, v57
	v_add_f32 v188, v188, v54
	v_add_f32 v188, v188, v55
	s_waitcnt lgkmcnt(8)
	v_mfma_f32_32x32x16_bf16 v[80:95], v[154:157], v[116:119], v[80:95]
	ds_read_b64_tr_b16 v[150:151], v192 offset:0
	ds_read_b64_tr_b16 v[152:153], v192 offset:1024
	v_cvt_pk_bf16_f32 v51, v54, v55
	v_and_b32 v51, v51, v210
	v_max3_f32 v211, v211, v58, v59
	v_exp_f32 v58, v58
	v_exp_f32 v59, v59
	v_add_f32 v188, v188, v56
	v_add_f32 v188, v188, v57
	v_cvt_pk_bf16_f32 v52, v56, v57
	v_and_b32 v52, v52, v210
	v_max3_f32 v211, v211, v60, v61
	v_exp_f32 v60, v60
	v_exp_f32 v61, v61
	v_add_f32 v188, v188, v58
	v_add_f32 v188, v188, v59
	s_waitcnt lgkmcnt(9)
	v_mfma_f32_32x32x16_bf16 v[96:111], v[158:161], v[116:119], v[96:111]
	ds_write_b128 v193, v[10:13] offset:9216
	ds_read_b64_tr_b16 v[154:155], v191 offset:2048
	ds_read_b64_tr_b16 v[156:157], v191 offset:3072
	v_cvt_pk_bf16_f32 v53, v58, v59
	v_and_b32 v53, v53, v210
	v_max3_f32 v211, v211, v62, v63
	v_exp_f32 v62, v62
	v_exp_f32 v63, v63
	v_add_f32 v188, v188, v60
	v_add_f32 v188, v188, v61
	v_cvt_pk_bf16_f32 v54, v60, v61
	v_and_b32 v54, v54, v210
	v_add_f32 v188, v188, v62
	v_add_f32 v188, v188, v63
	v_cvt_pk_bf16_f32 v55, v62, v63
	v_and_b32 v55, v55, v210
	v_max3_f32 v211, v211, v64, v65
	s_waitcnt lgkmcnt(11)
	v_mfma_f32_32x32x16_bf16 v[80:95], v[162:165], v[120:123], v[80:95]
	ds_read_b64_tr_b16 v[158:159], v192 offset:2048
	ds_read_b64_tr_b16 v[160:161], v192 offset:3072
	v_exp_f32 v64, v64
	v_exp_f32 v65, v65
	v_max3_f32 v211, v211, v66, v67
	v_exp_f32 v66, v66
	v_exp_f32 v67, v67
	v_add_f32 v188, v188, v64
	v_add_f32 v188, v188, v65
	v_cvt_pk_bf16_f32 v64, v64, v65
	v_and_b32 v64, v64, v210
	v_max3_f32 v211, v211, v68, v69
	v_exp_f32 v68, v68
	v_exp_f32 v69, v69
	v_add_f32 v188, v188, v66
	v_add_f32 v188, v188, v67
	s_waitcnt lgkmcnt(12)
	v_mfma_f32_32x32x16_bf16 v[96:111], v[166:169], v[120:123], v[96:111]
	ds_write_b128 v200, v[6:9]
	ds_read_b64_tr_b16 v[162:163], v191 offset:4096
	ds_read_b64_tr_b16 v[164:165], v191 offset:5120
	v_cvt_pk_bf16_f32 v65, v66, v67
	v_and_b32 v65, v65, v210
	v_max3_f32 v211, v211, v70, v71
	v_exp_f32 v70, v70
	v_exp_f32 v71, v71
	v_add_f32 v188, v188, v68
	v_add_f32 v188, v188, v69
	v_cvt_pk_bf16_f32 v66, v68, v69
	v_and_b32 v66, v66, v210
	v_max3_f32 v211, v211, v72, v73
	v_exp_f32 v72, v72
	v_exp_f32 v73, v73
	v_add_f32 v188, v188, v70
	v_add_f32 v188, v188, v71
	s_waitcnt lgkmcnt(14)
	v_mfma_f32_32x32x16_bf16 v[80:95], v[170:173], v[124:127], v[80:95]
	ds_read_b64_tr_b16 v[166:167], v192 offset:4096
	ds_read_b64_tr_b16 v[168:169], v192 offset:5120
	v_cvt_pk_bf16_f32 v67, v70, v71
	v_and_b32 v67, v67, v210
	v_max3_f32 v211, v211, v74, v75
	v_exp_f32 v74, v74
	v_exp_f32 v75, v75
	v_add_f32 v188, v188, v72
	v_add_f32 v188, v188, v73
	v_cvt_pk_bf16_f32 v68, v72, v73
	v_and_b32 v68, v68, v210
	v_max3_f32 v211, v211, v76, v77
	v_exp_f32 v76, v76
	v_exp_f32 v77, v77
	v_add_f32 v188, v188, v74
	v_add_f32 v188, v188, v75
	s_waitcnt lgkmcnt(15)
	v_mfma_f32_32x32x16_bf16 v[96:111], v[174:177], v[124:127], v[96:111]
	ds_write_b128 v200, v[136:139] offset:8192
	ds_read_b64_tr_b16 v[170:171], v191 offset:6144
	ds_read_b64_tr_b16 v[172:173], v191 offset:7168
	v_cvt_pk_bf16_f32 v69, v74, v75
	v_and_b32 v69, v69, v210
	v_max3_f32 v211, v211, v78, v79
	v_exp_f32 v78, v78
	v_exp_f32 v79, v79
	v_add_f32 v188, v188, v76
	v_add_f32 v188, v188, v77
	v_cvt_pk_bf16_f32 v70, v76, v77
	v_and_b32 v70, v70, v210
	v_add_f32 v188, v188, v78
	v_add_f32 v188, v188, v79
	v_cvt_pk_bf16_f32 v71, v78, v79
	v_and_b32 v71, v71, v210
	v_and_b32 v188, v188, v210
	v_add_f32 v206, v206, v188
	s_cmp_eq_u32 s13, 2
	s_cselect_b32 s8, 0x19800, 0
	s_sub_u32 s8, 0x8800, s8
	s_add_u32 s13, s13, 1
	s_cmp_eq_u32 s13, 3
	s_cselect_b32 s13, 0, s13
	s_waitcnt lgkmcnt(0)
	s_add_u32 s9, s26, 2
	s_cmp_lt_u32 s9, s30
	s_cbranch_scc0 .Lat1_mid3
	global_load_dwordx4 v[2:5], v184, s[52:53]
	global_load_dwordx4 v[6:9], v184, s[52:53] offset:1024
	global_load_dwordx4 v[10:13], v185, s[52:53]
	global_load_dwordx4 v[136:139], v185, s[52:53] offset:1024
	s_add_u32 s52, s52, 0x100000
	s_addc_u32 s53, s53, 0
; template <int TYPE>
; __device__ __forceinline__ void attn_item(const Ctx& a, int b, int h, int qt, LAS unsigned char* lds) {
;     ...
;             float ps = 0.f;
; #pragma unroll
;             for (int kb = 0; kb < 2; ++kb)
; #pragma unroll
;                 for (int r = 0; r < 16; ++r) { float p = __builtin_amdgcn_exp2f(s[sub][kb][r]); s[sub][kb][r] = p; ps += p; }
;             lrun += ps;
; #pragma unroll
;             for (int kb = 0; kb < 2; ++kb)
; #pragma unroll
;                 for (int c = 0; c < 2; ++c) {
;                     bf16x8 pb = pack8(s[sub][kb], c);
; #pragma unroll
;                     for (int db = 0; db < 2; ++db)
;                         oacc[db] = __builtin_amdgcn_mfma_f32_32x32x16_bf16(lds_a2(VT + (db * 32 + l32) * VLD + sub * 64 + kb * 32 + c * 16 + hb * 4), pb, oacc[db], 0, 0, 0);
;                 }
;             if (rare) {
;                 lrun *= fpost;
; #pragma unroll
;                 for (int db = 0; db < 2; ++db)
; #pragma unroll
;                     for (int r = 0; r < 16; ++r) oacc[db][r] *= fpost;
;             }
.Lat1_mid3:
	v_add_u32 v193, s8, v193
	v_add_u32 v200, s8, v200
	s_barrier
	s_nop 7
	s_nop 0
	v_mfma_f32_32x32x16_bf16 v[16:31], v[146:149], v[48:51], v[16:31]
	ds_read_b64_tr_b16 v[174:175], v192 offset:6144
	ds_read_b64_tr_b16 v[176:177], v192 offset:7168
	v_max3_f32 v211, v211, v80, v81
	v_exp_f32 v80, v80
	v_exp_f32 v81, v81
	v_max3_f32 v211, v211, v82, v83
	v_exp_f32 v82, v82
	v_exp_f32 v83, v83
	v_add_f32 v188, v80, v81
	v_cvt_pk_bf16_f32 v80, v80, v81
	v_and_b32 v80, v80, v210
	v_max3_f32 v211, v211, v84, v85
	v_exp_f32 v84, v84
	v_exp_f32 v85, v85
	v_add_f32 v188, v188, v82
	v_add_f32 v188, v188, v83
	v_mfma_f32_32x32x16_bf16 v[32:47], v[150:153], v[48:51], v[32:47]
	ds_read_b64_tr_b16 v[146:147], v191 offset:8192
	ds_read_b64_tr_b16 v[148:149], v191 offset:9216
	v_cvt_pk_bf16_f32 v81, v82, v83
	v_and_b32 v81, v81, v210
	v_max3_f32 v211, v211, v86, v87
	v_exp_f32 v86, v86
	v_exp_f32 v87, v87
	v_add_f32 v188, v188, v84
	v_add_f32 v188, v188, v85
	v_cvt_pk_bf16_f32 v82, v84, v85
	v_and_b32 v82, v82, v210
	v_max3_f32 v211, v211, v88, v89
	v_exp_f32 v88, v88
	v_exp_f32 v89, v89
	v_add_f32 v188, v188, v86
	v_add_f32 v188, v188, v87
	v_mfma_f32_32x32x16_bf16 v[16:31], v[154:157], v[52:55], v[16:31]
	ds_read_b64_tr_b16 v[150:151], v192 offset:8192
	ds_read_b64_tr_b16 v[152:153], v192 offset:9216
	v_cvt_pk_bf16_f32 v83, v86, v87
	v_and_b32 v83, v83, v210
	v_max3_f32 v211, v211, v90, v91
	v_exp_f32 v90, v90
	v_exp_f32 v91, v91
	v_add_f32 v188, v188, v88
	v_add_f32 v188, v188, v89
	v_cvt_pk_bf16_f32 v84, v88, v89
	v_and_b32 v84, v84, v210
	v_max3_f32 v211, v211, v92, v93
	v_exp_f32 v92, v92
	v_exp_f32 v93, v93
	v_add_f32 v188, v188, v90
	v_add_f32 v188, v188, v91
	v_mfma_f32_32x32x16_bf16 v[32:47], v[158:161], v[52:55], v[32:47]
	ds_read_b64_tr_b16 v[154:155], v191 offset:10240
	ds_read_b64_tr_b16 v[156:157], v191 offset:11264
	v_cvt_pk_bf16_f32 v85, v90, v91
	v_and_b32 v85, v85, v210
	v_max3_f32 v211, v211, v94, v95
	v_exp_f32 v94, v94
	v_exp_f32 v95, v95
	v_add_f32 v188, v188, v92
	v_add_f32 v188, v188, v93
	v_cvt_pk_bf16_f32 v86, v92, v93
	v_and_b32 v86, v86, v210
	v_add_f32 v188, v188, v94
	v_add_f32 v188, v188, v95
	v_cvt_pk_bf16_f32 v87, v94, v95
	v_and_b32 v87, v87, v210
	v_max3_f32 v211, v211, v96, v97
	v_mfma_f32_32x32x16_bf16 v[16:31], v[162:165], v[64:67], v[16:31]
	ds_read_b64_tr_b16 v[158:159], v192 offset:10240
	ds_read_b64_tr_b16 v[160:161], v192 offset:11264
	v_exp_f32 v96, v96
	v_exp_f32 v97, v97
	v_max3_f32 v211, v211, v98, v99
	v_exp_f32 v98, v98
	v_exp_f32 v99, v99
	v_add_f32 v188, v188, v96
	v_add_f32 v188, v188, v97
	v_cvt_pk_bf16_f32 v96, v96, v97
	v_and_b32 v96, v96, v210
	v_max3_f32 v211, v211, v100, v101
	v_exp_f32 v100, v100
	v_exp_f32 v101, v101
	v_add_f32 v188, v188, v98
	v_add_f32 v188, v188, v99
	v_mfma_f32_32x32x16_bf16 v[32:47], v[166:169], v[64:67], v[32:47]
	ds_read_b64_tr_b16 v[162:163], v191 offset:12288
	ds_read_b64_tr_b16 v[164:165], v191 offset:13312
	v_cvt_pk_bf16_f32 v97, v98, v99
	v_and_b32 v97, v97, v210
	v_max3_f32 v211, v211, v102, v103
	v_exp_f32 v102, v102
	v_exp_f32 v103, v103
	v_add_f32 v188, v188, v100
	v_add_f32 v188, v188, v101
	v_cvt_pk_bf16_f32 v98, v100, v101
	v_and_b32 v98, v98, v210
	v_max3_f32 v211, v211, v104, v105
	v_exp_f32 v104, v104
	v_exp_f32 v105, v105
	v_add_f32 v188, v188, v102
	v_add_f32 v188, v188, v103
	v_mfma_f32_32x32x16_bf16 v[16:31], v[170:173], v[68:71], v[16:31]
	ds_read_b64_tr_b16 v[166:167], v192 offset:12288
	ds_read_b64_tr_b16 v[168:169], v192 offset:13312
	v_cvt_pk_bf16_f32 v99, v102, v103
	v_and_b32 v99, v99, v210
	v_max3_f32 v211, v211, v106, v107
	v_exp_f32 v106, v106
	v_exp_f32 v107, v107
	v_add_f32 v188, v188, v104
	v_add_f32 v188, v188, v105
	v_cvt_pk_bf16_f32 v100, v104, v105
	v_and_b32 v100, v100, v210
	v_max3_f32 v211, v211, v108, v109
	v_exp_f32 v108, v108
	v_exp_f32 v109, v109
	v_add_f32 v188, v188, v106
	v_add_f32 v188, v188, v107
	s_waitcnt lgkmcnt(12)
	v_mfma_f32_32x32x16_bf16 v[32:47], v[174:177], v[68:71], v[32:47]
	ds_read_b64_tr_b16 v[170:171], v191 offset:14336
	ds_read_b64_tr_b16 v[172:173], v191 offset:15360
	v_cvt_pk_bf16_f32 v101, v106, v107
	v_and_b32 v101, v101, v210
	v_max3_f32 v211, v211, v110, v111
	v_exp_f32 v110, v110
	v_exp_f32 v111, v111
	v_add_f32 v188, v188, v108
	v_add_f32 v188, v188, v109
	v_cvt_pk_bf16_f32 v102, v108, v109
	v_and_b32 v102, v102, v210
	v_add_f32 v188, v188, v110
	v_add_f32 v188, v188, v111
	v_cvt_pk_bf16_f32 v103, v110, v111
	v_and_b32 v103, v103, v210
	v_and_b32 v188, v188, v210
	v_add_f32 v206, v206, v188
	s_waitcnt lgkmcnt(12)
	v_mfma_f32_32x32x16_bf16 v[16:31], v[146:149], v[80:83], v[16:31]
	ds_read_b64_tr_b16 v[174:175], v192 offset:14336
	ds_read_b64_tr_b16 v[176:177], v192 offset:15360
	s_waitcnt lgkmcnt(12)
	v_mfma_f32_32x32x16_bf16 v[32:47], v[150:153], v[80:83], v[32:47]
	s_waitcnt lgkmcnt(10)
	v_mfma_f32_32x32x16_bf16 v[16:31], v[154:157], v[84:87], v[16:31]
	s_waitcnt lgkmcnt(8)
	v_mfma_f32_32x32x16_bf16 v[32:47], v[158:161], v[84:87], v[32:47]
	s_waitcnt lgkmcnt(6)
	v_mfma_f32_32x32x16_bf16 v[16:31], v[162:165], v[96:99], v[16:31]
	s_waitcnt lgkmcnt(4)
	v_mfma_f32_32x32x16_bf16 v[32:47], v[166:169], v[96:99], v[32:47]
	s_waitcnt lgkmcnt(2)
	v_mfma_f32_32x32x16_bf16 v[16:31], v[170:173], v[100:103], v[16:31]
	s_waitcnt lgkmcnt(0)
	v_mfma_f32_32x32x16_bf16 v[32:47], v[174:177], v[100:103], v[32:47]
	v_cndmask_b32_e64 v211, v0, v211, s[38:39]
	v_cmp_gt_f32_e64 s[40:41], v211, v207
	s_cmp_lg_u64 s[40:41], 0
	s_cbranch_scc0 .Lat1_pairend
	v_mov_b32 v1, v211
	s_nop 1
	v_permlane32_swap_b32 v1, v211
	v_max_f32 v1, v1, v211
	v_cmp_gt_f32 vcc, v1, v207
	s_nop 1
	v_cndmask_b32 v14, v205, v1, vcc
	v_sub_f32 v15, v205, v14
	v_exp_f32 v15, v15
	v_mov_b32 v205, v14
	v_add_f32 v207, 0x41000000, v14
	v_mul_f32 v16, v16, v15
	v_mul_f32 v17, v17, v15
	v_mul_f32 v18, v18, v15
	v_mul_f32 v19, v19, v15
	v_mul_f32 v20, v20, v15
	v_mul_f32 v21, v21, v15
	v_mul_f32 v22, v22, v15
	v_mul_f32 v23, v23, v15
	v_mul_f32 v24, v24, v15
	v_mul_f32 v25, v25, v15
	v_mul_f32 v26, v26, v15
	v_mul_f32 v27, v27, v15
	v_mul_f32 v28, v28, v15
	v_mul_f32 v29, v29, v15
	v_mul_f32 v30, v30, v15
	v_mul_f32 v31, v31, v15
	v_mul_f32 v32, v32, v15
	v_mul_f32 v33, v33, v15
	v_mul_f32 v34, v34, v15
	v_mul_f32 v35, v35, v15
	v_mul_f32 v36, v36, v15
	v_mul_f32 v37, v37, v15
	v_mul_f32 v38, v38, v15
	v_mul_f32 v39, v39, v15
	v_mul_f32 v40, v40, v15
	v_mul_f32 v41, v41, v15
	v_mul_f32 v42, v42, v15
	v_mul_f32 v43, v43, v15
	v_mul_f32 v44, v44, v15
	v_mul_f32 v45, v45, v15
	v_mul_f32 v46, v46, v15
	v_mul_f32 v47, v47, v15
	v_mul_f32 v206, v206, v15
	v_cmp_neq_f32_e64 s[36:37], 0, v205
	s_branch .Lat1_pairend
